# v19
# baseline (speedup 1.0000x reference)
.LBB0_947:
	v_readlane_b32 s4, v255, 2
	v_readlane_b32 s5, v255, 3
	s_lshl_b64 s[4:5], s[4:5], 2
	s_add_u32 s4, s88, s4
	s_addc_u32 s5, s89, s5
	s_add_u32 s10, s4, 0xc418000
	s_addc_u32 s11, s5, 0
	s_add_u32 s20, s88, 0x1bedb700
	s_addc_u32 s21, s89, 0
	s_add_u32 s22, s88, 0x1fadb700
	s_addc_u32 s23, s89, 0
	s_add_u32 s24, s88, 0x1fcdb700
	s_addc_u32 s25, s89, 0
	s_add_u32 s26, s88, 0x1e6db700
	s_addc_u32 s27, s89, 0
	v_or_b32_e32 v0, s34, v152
	s_add_u32 s28, s88, 0x1f0db700
	v_cmp_eq_u32_e64 s[4:5], 0, v0
	s_addc_u32 s29, s89, 0
	s_waitcnt vmcnt(0) lgkmcnt(0)
	s_barrier
	v_readlane_b32 s100, v255, 8
	s_nop 3
	s_cmp_ge_u32 s100, 4
	s_cbranch_scc0 .Lmy_att_prio
	s_setprio 1
.Lmy_att_prio:
	s_branch .LBB0_950
.LBB0_948:
	s_or_b64 exec, exec, s[8:9]
	s_waitcnt lgkmcnt(0)
	v_add_u32_e32 v72, v181, v176
	ds_read_b128 v[64:67], v72
	ds_read_b128 v[68:71], v72 offset:32
	s_add_u32 s8, s88, s14
	s_addc_u32 s9, s89, s15
	s_lshl_b64 s[6:7], s[12:13], 1
	s_waitcnt lgkmcnt(1)
	v_rcp_f32_e32 v73, v64
	v_rcp_f32_e32 v74, v65
	v_rcp_f32_e32 v75, v66
	v_rcp_f32_e32 v76, v67
	ds_read_b128 v[64:67], v72 offset:64
	s_add_u32 s6, s8, s6
	v_ashrrev_i32_e32 v181, 31, v180
	s_addc_u32 s7, s9, s7
	s_waitcnt lgkmcnt(1)
	v_rcp_f32_e32 v77, v68
	v_rcp_f32_e32 v78, v69
	v_rcp_f32_e32 v79, v70
	v_rcp_f32_e32 v80, v71
	ds_read_b128 v[68:71], v72 offset:96
	s_waitcnt lgkmcnt(1)
	v_rcp_f32_e32 v72, v64
	v_rcp_f32_e32 v81, v65
	v_lshlrev_b64 v[64:65], 12, v[180:181]
	v_lshl_add_u64 v[64:65], s[6:7], 0, v[64:65]
	v_lshlrev_b32_e32 v178, 1, v177
	v_rcp_f32_e32 v82, v66
	v_rcp_f32_e32 v83, v67
	v_lshlrev_b32_e32 v66, 14, v190
	v_lshl_add_u64 v[64:65], v[64:65], 0, v[178:179]
	v_mov_b32_e32 v67, v179
	v_lshl_add_u64 v[64:65], v[64:65], 0, v[66:67]
	s_mov_b64 s[6:7], 0xc4dbb00
	v_lshl_add_u64 v[66:67], v[64:65], 0, s[6:7]
	s_mov_b32 s6, 0xc4db000
	s_waitcnt lgkmcnt(0)
	v_rcp_f32_e32 v84, v68
	v_mul_f32_e32 v0, v0, v73
	v_add_co_u32_e32 v68, vcc, s6, v64
	v_rcp_f32_e32 v85, v69
	v_cvt_pk_bf16_f32 v0, v0, v179
	s_nop 0
	v_addc_co_u32_e32 v69, vcc, 0, v65, vcc
	flat_store_short v[68:69], v0 offset:2816
	v_mul_f32_e32 v0, v48, v73
	v_cvt_pk_bf16_f32 v0, v0, v179
	flat_store_short v[66:67], v0 offset:64
	v_mul_f32_e32 v0, v32, v73
	v_cvt_pk_bf16_f32 v0, v0, v179
	flat_store_short v[66:67], v0 offset:128
	v_mul_f32_e32 v0, v16, v73
	v_cvt_pk_bf16_f32 v0, v0, v179
	flat_store_short v[66:67], v0 offset:192
	v_mul_f32_e32 v0, v1, v74
	s_mov_b32 s6, 0xc4dc000
	v_cvt_pk_bf16_f32 v16, v0, v179
	v_add_co_u32_e32 v0, vcc, s6, v64
	s_mov_b32 s6, 0xc4dd000
	s_nop 0
	v_addc_co_u32_e32 v1, vcc, 0, v65, vcc
	flat_store_short v[0:1], v16 offset:2816
	v_mul_f32_e32 v16, v49, v74
	v_cvt_pk_bf16_f32 v16, v16, v179
	flat_store_short v[0:1], v16 offset:2880
	v_mul_f32_e32 v16, v33, v74
	v_cvt_pk_bf16_f32 v16, v16, v179
	flat_store_short v[0:1], v16 offset:2944
	v_mul_f32_e32 v16, v17, v74
	v_cvt_pk_bf16_f32 v16, v16, v179
	flat_store_short v[0:1], v16 offset:3008
	v_mul_f32_e32 v0, v2, v75
	v_cvt_pk_bf16_f32 v2, v0, v179
	v_add_co_u32_e32 v0, vcc, s6, v64
	s_mov_b32 s6, 0xc4de000
	s_nop 0
	v_addc_co_u32_e32 v1, vcc, 0, v65, vcc
	flat_store_short v[0:1], v2 offset:2816
	v_mul_f32_e32 v2, v50, v75
	v_cvt_pk_bf16_f32 v2, v2, v179
	flat_store_short v[0:1], v2 offset:2880
	v_mul_f32_e32 v2, v34, v75
	v_cvt_pk_bf16_f32 v2, v2, v179
	flat_store_short v[0:1], v2 offset:2944
	v_mul_f32_e32 v2, v18, v75
	v_cvt_pk_bf16_f32 v2, v2, v179
	flat_store_short v[0:1], v2 offset:3008
	v_mul_f32_e32 v0, v3, v76
	v_cvt_pk_bf16_f32 v2, v0, v179
	v_add_co_u32_e32 v0, vcc, s6, v64
	s_mov_b32 s6, 0xc4e3000
	s_nop 0
	v_addc_co_u32_e32 v1, vcc, 0, v65, vcc
	flat_store_short v[0:1], v2 offset:2816
	v_mul_f32_e32 v2, v51, v76
	v_cvt_pk_bf16_f32 v2, v2, v179
	flat_store_short v[0:1], v2 offset:2880
	v_mul_f32_e32 v2, v35, v76
	v_cvt_pk_bf16_f32 v2, v2, v179
	flat_store_short v[0:1], v2 offset:2944
	v_mul_f32_e32 v2, v19, v76
	v_cvt_pk_bf16_f32 v2, v2, v179
	flat_store_short v[0:1], v2 offset:3008
	v_mul_f32_e32 v0, v4, v77
	v_cvt_pk_bf16_f32 v2, v0, v179
	v_add_co_u32_e32 v0, vcc, s6, v64
	s_mov_b32 s6, 0xc4e4000
	s_nop 0
	v_addc_co_u32_e32 v1, vcc, 0, v65, vcc
	flat_store_short v[0:1], v2 offset:2816
	v_mul_f32_e32 v2, v52, v77
	v_cvt_pk_bf16_f32 v2, v2, v179
	flat_store_short v[0:1], v2 offset:2880
	v_mul_f32_e32 v2, v36, v77
	v_cvt_pk_bf16_f32 v2, v2, v179
	flat_store_short v[0:1], v2 offset:2944
	v_mul_f32_e32 v2, v20, v77
	v_cvt_pk_bf16_f32 v2, v2, v179
	flat_store_short v[0:1], v2 offset:3008
	v_mul_f32_e32 v0, v5, v78
	v_cvt_pk_bf16_f32 v2, v0, v179
	v_add_co_u32_e32 v0, vcc, s6, v64
	s_mov_b32 s6, 0xc4e5000
	s_nop 0
	v_addc_co_u32_e32 v1, vcc, 0, v65, vcc
	flat_store_short v[0:1], v2 offset:2816
	v_mul_f32_e32 v2, v53, v78
	v_cvt_pk_bf16_f32 v2, v2, v179
	flat_store_short v[0:1], v2 offset:2880
	v_mul_f32_e32 v2, v37, v78
	v_cvt_pk_bf16_f32 v2, v2, v179
	flat_store_short v[0:1], v2 offset:2944
	v_mul_f32_e32 v2, v21, v78
	v_cvt_pk_bf16_f32 v2, v2, v179
	flat_store_short v[0:1], v2 offset:3008
	v_mul_f32_e32 v0, v6, v79
	v_cvt_pk_bf16_f32 v2, v0, v179
	v_add_co_u32_e32 v0, vcc, s6, v64
	s_mov_b32 s6, 0xc4e6000
	s_nop 0
	v_addc_co_u32_e32 v1, vcc, 0, v65, vcc
	flat_store_short v[0:1], v2 offset:2816
	v_mul_f32_e32 v2, v54, v79
	v_cvt_pk_bf16_f32 v2, v2, v179
	flat_store_short v[0:1], v2 offset:2880
	v_mul_f32_e32 v2, v38, v79
	v_cvt_pk_bf16_f32 v2, v2, v179
	flat_store_short v[0:1], v2 offset:2944
	v_mul_f32_e32 v2, v22, v79
	v_cvt_pk_bf16_f32 v2, v2, v179
	flat_store_short v[0:1], v2 offset:3008
	v_mul_f32_e32 v0, v7, v80
	v_cvt_pk_bf16_f32 v2, v0, v179
	v_add_co_u32_e32 v0, vcc, s6, v64
	s_mov_b32 s6, 0xc4eb000
	s_nop 0
	v_addc_co_u32_e32 v1, vcc, 0, v65, vcc
	flat_store_short v[0:1], v2 offset:2816
	v_mul_f32_e32 v2, v55, v80
	v_cvt_pk_bf16_f32 v2, v2, v179
	flat_store_short v[0:1], v2 offset:2880
	v_mul_f32_e32 v2, v39, v80
	v_cvt_pk_bf16_f32 v2, v2, v179
	flat_store_short v[0:1], v2 offset:2944
	v_mul_f32_e32 v2, v23, v80
	v_cvt_pk_bf16_f32 v2, v2, v179
	flat_store_short v[0:1], v2 offset:3008
	v_mul_f32_e32 v0, v8, v72
	v_cvt_pk_bf16_f32 v2, v0, v179
	v_add_co_u32_e32 v0, vcc, s6, v64
	s_mov_b32 s6, 0xc4ec000
	s_nop 0
	v_addc_co_u32_e32 v1, vcc, 0, v65, vcc
	flat_store_short v[0:1], v2 offset:2816
	v_mul_f32_e32 v2, v56, v72
	v_cvt_pk_bf16_f32 v2, v2, v179
	flat_store_short v[0:1], v2 offset:2880
	v_mul_f32_e32 v2, v40, v72
	v_cvt_pk_bf16_f32 v2, v2, v179
	flat_store_short v[0:1], v2 offset:2944
	v_mul_f32_e32 v2, v24, v72
	v_cvt_pk_bf16_f32 v2, v2, v179
	flat_store_short v[0:1], v2 offset:3008
	v_mul_f32_e32 v0, v9, v81
	v_cvt_pk_bf16_f32 v2, v0, v179
	v_add_co_u32_e32 v0, vcc, s6, v64
	s_mov_b32 s6, 0xc4ed000
	s_nop 0
	v_addc_co_u32_e32 v1, vcc, 0, v65, vcc
	flat_store_short v[0:1], v2 offset:2816
	v_mul_f32_e32 v2, v57, v81
	v_cvt_pk_bf16_f32 v2, v2, v179
	flat_store_short v[0:1], v2 offset:2880
	v_mul_f32_e32 v2, v41, v81
	v_cvt_pk_bf16_f32 v2, v2, v179
	flat_store_short v[0:1], v2 offset:2944
	v_mul_f32_e32 v2, v25, v81
	v_cvt_pk_bf16_f32 v2, v2, v179
	flat_store_short v[0:1], v2 offset:3008
	v_mul_f32_e32 v0, v10, v82
	v_cvt_pk_bf16_f32 v2, v0, v179
	v_add_co_u32_e32 v0, vcc, s6, v64
	s_mov_b32 s6, 0xc4ee000
	s_nop 0
	v_addc_co_u32_e32 v1, vcc, 0, v65, vcc
	flat_store_short v[0:1], v2 offset:2816
	v_mul_f32_e32 v2, v58, v82
	v_cvt_pk_bf16_f32 v2, v2, v179
	flat_store_short v[0:1], v2 offset:2880
	v_mul_f32_e32 v2, v42, v82
	v_cvt_pk_bf16_f32 v2, v2, v179
	flat_store_short v[0:1], v2 offset:2944
	v_mul_f32_e32 v2, v26, v82
	v_cvt_pk_bf16_f32 v2, v2, v179
	flat_store_short v[0:1], v2 offset:3008
	v_mul_f32_e32 v0, v11, v83
	v_cvt_pk_bf16_f32 v2, v0, v179
	v_add_co_u32_e32 v0, vcc, s6, v64
	s_mov_b32 s6, 0xc4f3000
	s_nop 0
	v_addc_co_u32_e32 v1, vcc, 0, v65, vcc
	flat_store_short v[0:1], v2 offset:2816
	v_mul_f32_e32 v2, v59, v83
	v_cvt_pk_bf16_f32 v2, v2, v179
	flat_store_short v[0:1], v2 offset:2880
	v_mul_f32_e32 v2, v43, v83
	v_cvt_pk_bf16_f32 v2, v2, v179
	flat_store_short v[0:1], v2 offset:2944
	v_mul_f32_e32 v2, v27, v83
	v_cvt_pk_bf16_f32 v2, v2, v179
	flat_store_short v[0:1], v2 offset:3008
	v_mul_f32_e32 v0, v12, v84
	v_cvt_pk_bf16_f32 v2, v0, v179
	v_add_co_u32_e32 v0, vcc, s6, v64
	s_mov_b32 s6, 0xc4f4000
	s_nop 0
	v_addc_co_u32_e32 v1, vcc, 0, v65, vcc
	flat_store_short v[0:1], v2 offset:2816
	v_mul_f32_e32 v2, v60, v84
	v_cvt_pk_bf16_f32 v2, v2, v179
	flat_store_short v[0:1], v2 offset:2880
	v_mul_f32_e32 v2, v44, v84
	v_cvt_pk_bf16_f32 v2, v2, v179
	flat_store_short v[0:1], v2 offset:2944
	v_mul_f32_e32 v2, v28, v84
	v_cvt_pk_bf16_f32 v2, v2, v179
	flat_store_short v[0:1], v2 offset:3008
	v_mul_f32_e32 v0, v13, v85
	v_cvt_pk_bf16_f32 v2, v0, v179
	v_add_co_u32_e32 v0, vcc, s6, v64
	v_rcp_f32_e32 v70, v70
	s_nop 0
	v_addc_co_u32_e32 v1, vcc, 0, v65, vcc
	flat_store_short v[0:1], v2 offset:2816
	v_mul_f32_e32 v2, v61, v85
	v_cvt_pk_bf16_f32 v2, v2, v179
	flat_store_short v[0:1], v2 offset:2880
	v_mul_f32_e32 v2, v45, v85
	v_cvt_pk_bf16_f32 v2, v2, v179
	flat_store_short v[0:1], v2 offset:2944
	v_mul_f32_e32 v2, v29, v85
	v_cvt_pk_bf16_f32 v2, v2, v179
	flat_store_short v[0:1], v2 offset:3008
	v_mul_f32_e32 v0, v14, v70
	s_mov_b32 s6, 0xc4f5000
	v_cvt_pk_bf16_f32 v2, v0, v179
	v_add_co_u32_e32 v0, vcc, s6, v64
	v_rcp_f32_e32 v71, v71
	s_nop 0
	v_addc_co_u32_e32 v1, vcc, 0, v65, vcc
	flat_store_short v[0:1], v2 offset:2816
	v_mul_f32_e32 v2, v62, v70
	v_cvt_pk_bf16_f32 v2, v2, v179
	flat_store_short v[0:1], v2 offset:2880
	v_mul_f32_e32 v2, v46, v70
	v_cvt_pk_bf16_f32 v2, v2, v179
	flat_store_short v[0:1], v2 offset:2944
	v_mul_f32_e32 v2, v30, v70
	v_cvt_pk_bf16_f32 v2, v2, v179
	flat_store_short v[0:1], v2 offset:3008
	v_mul_f32_e32 v0, v15, v71
	s_mov_b32 s6, 0xc4f6000
	v_cvt_pk_bf16_f32 v2, v0, v179
	v_add_co_u32_e32 v0, vcc, s6, v64
	s_mov_b64 s[6:7], 0
	s_nop 0
	v_addc_co_u32_e32 v1, vcc, 0, v65, vcc
	flat_store_short v[0:1], v2 offset:2816
	v_mul_f32_e32 v2, v63, v71
	v_cvt_pk_bf16_f32 v2, v2, v179
	flat_store_short v[0:1], v2 offset:2880
	v_mul_f32_e32 v2, v47, v71
	v_cvt_pk_bf16_f32 v2, v2, v179
	flat_store_short v[0:1], v2 offset:2944
	v_mul_f32_e32 v2, v31, v71
	v_cvt_pk_bf16_f32 v2, v2, v179
	flat_store_short v[0:1], v2 offset:3008
	s_waitcnt lgkmcnt(0)
	s_barrier

.LBB0_976:
	s_setprio 0
	v_readlane_b32 s5, v255, 8
	v_readlane_b32 s4, v255, 7
	s_mov_b32 s86, s5
	s_nop 0
	v_writelane_b32 v255, s4, 7
	s_getreg_b32 s4, hwreg(HW_REG_XCC_ID, 0, 4)
	v_mbcnt_lo_u32_b32 v0, -1, 0
	v_mbcnt_hi_u32_b32 v0, -1, v0
	s_waitcnt vmcnt(0)
	s_nop 0
	v_lshl_or_b32 v0, s5, 6, v0
	v_cmp_eq_u32_e32 vcc, 0, v0
	s_barrier
	s_and_saveexec_b64 s[56:57], vcc
	s_cbranch_execz .LBB0_1020
	v_readlane_b32 s5, v254, 31
	s_waitcnt vmcnt(0) expcnt(0) lgkmcnt(0)
	s_and_b32 s39, s4, 15
	v_mov_b32_e32 v0, s5
	ds_read_b32 v2, v0
	v_readlane_b32 s5, v254, 32
	s_waitcnt lgkmcnt(0)
	v_cmp_ne_u32_e32 vcc, 0, v2
	v_mov_b32_e32 v0, s5
	ds_read_b32 v0, v0
	s_cbranch_vccnz .LBB0_991
	s_add_u32 s4, s88, 0xc418300
	s_addc_u32 s5, s89, 0
	s_add_u32 s6, s88, 0xc418500
	s_addc_u32 s7, s89, 0
	s_add_u32 s8, s88, 0xc418600
	s_addc_u32 s9, s89, 0
	s_add_u32 s10, s88, 0xc418700
	s_addc_u32 s11, s89, 0
	s_add_u32 s12, s88, 0xc418800
	s_addc_u32 s13, s89, 0
	s_add_u32 s14, s88, 0xc418900
	s_addc_u32 s15, s89, 0
	s_add_u32 s16, s88, 0xc418a00
	s_addc_u32 s17, s89, 0
	s_add_u32 s18, s88, 0xc418b00
	s_addc_u32 s19, s89, 0
	s_add_u32 s20, s88, 0xc418c00
	s_addc_u32 s21, s89, 0
	s_add_u32 s22, s88, 0xc418d00
	s_addc_u32 s23, s89, 0
	s_add_u32 s24, s88, 0xc418e00
	s_addc_u32 s25, s89, 0
	s_add_u32 s26, s88, 0xc418f00
	s_addc_u32 s27, s89, 0
	s_add_u32 s28, s88, 0xc419000
	s_addc_u32 s29, s89, 0
	s_add_u32 s30, s88, 0xc419100
	s_addc_u32 s31, s89, 0
	s_add_u32 s34, s88, 0xc419200
	s_addc_u32 s35, s89, 0
	s_add_u32 s58, s88, 0xc419300
	s_addc_u32 s59, s89, 0
	s_add_u32 s60, s88, 0xc419400
	s_addc_u32 s61, s89, 0
	s_mov_b32 s82, 1
	s_mov_b64 s[62:63], 0
	s_branch .LBB0_981
